# rwkv_post loop: four ypart pair loads into own registers, one full wait per iteration instead of four
# speedup vs baseline: 1.0022x; 1.0022x over previous
; __device__ __forceinline__ float wave_sum(float v) { v = row16_allsum(v); v = rows_pair_sum(v); v = halves_pair_sum(v); return v; }
; __device__ __forceinline__ void rwkv_post(const Params& P, int l, int gw, int NGW, int lane) {
;     ...
;     for (int it0 = gw; it0 < T * 4; it0 += 4 * NGW) {
;         float y[4], r[4], k[4], v[4], g[4], lg[4], lb[4], rk[4];
; #pragma unroll
;         for (int q = 0; q < 4; ++q) { const int it = it0 + q * NGW; const size_t t = (size_t)(it >> 2); const int c = (it & 3) * 64 + lane;
;             y[q] = Y[t * 256 + c] + Y[((size_t)T + t) * 256 + c]; r[q] = RKV[t * 768 + c]; k[q] = RKV[t * 768 + 256 + c]; v[q] = RKV[t * 768 + 512 + c]; g[q] = G[t * 256 + c];
;             lg[q] = ln_g[c]; lb[q] = ln_b[c]; rk[q] = r_k[c]; }
; #pragma unroll
;         for (int q = 0; q < 4; ++q) { const int it = it0 + q * NGW; const size_t t = (size_t)(it >> 2); const int c = (it & 3) * 64 + lane;
;             const float mean = wave_sum(y[q]) * (1.0f / 64.0f);
.LBB0_62:
	v_ashrrev_i32_e32 v6, 2, v0
	s_movk_i32 s4, 0xc0
	v_ashrrev_i32_e32 v7, 31, v6
	v_and_or_b32 v28, v8, s4, v154
	v_lshlrev_b64 v[2:3], 10, v[6:7]
	v_lshlrev_b32_e32 v152, 2, v28
	v_or_b32_e32 v4, v2, v152
	v_mov_b32_e32 v5, v3
	v_lshl_add_u64 v[2:3], s[8:9], 0, v[2:3]
	v_lshl_add_u64 v[2:3], v[2:3], 0, v[152:153]
	v_add_co_u32_e32 v2, vcc, s28, v2
	v_lshl_add_u64 v[10:11], s[8:9], 0, v[4:5]
	s_nop 0
	v_addc_co_u32_e32 v3, vcc, 0, v3, vcc
	global_load_dword v60, v[10:11], off
	v_mov_b64_e32 v[12:13], s[10:11]
	global_load_dword v61, v[2:3], off
	v_add_u32_e32 v11, s22, v0
	v_add_u32_e32 v8, s33, v8
	v_mad_i64_i32 v[2:3], s[4:5], v6, s84, v[12:13]
	v_lshl_add_u64 v[2:3], v[2:3], 0, v[152:153]
	global_load_dword v36, v[2:3], off
	global_load_dword v37, v[2:3], off offset:1024
	global_load_dword v29, v[2:3], off offset:2048
	v_lshl_add_u64 v[2:3], s[12:13], 0, v[4:5]
	v_ashrrev_i32_e32 v4, 2, v11
	v_ashrrev_i32_e32 v5, 31, v4
	v_lshlrev_b64 v[0:1], 10, v[4:5]
	global_load_dword v30, v[2:3], off
	global_load_dword v14, v152, s[26:27]
	global_load_dword v9, v152, s[30:31]
	global_load_dword v10, v152, s[24:25]
	v_or_b32_e32 v2, v0, v152
	v_mov_b32_e32 v3, v1
	v_lshl_add_u64 v[0:1], s[8:9], 0, v[0:1]
	v_lshl_add_u64 v[0:1], v[0:1], 0, v[152:153]
	v_add_co_u32_e32 v0, vcc, s28, v0
	v_lshl_add_u64 v[16:17], s[8:9], 0, v[2:3]
	s_nop 0
	v_addc_co_u32_e32 v1, vcc, 0, v1, vcc
	global_load_dword v62, v[16:17], off
	v_add_u32_e32 v11, s22, v11
	global_load_dword v63, v[0:1], off
	v_lshlrev_b64 v[6:7], 11, v[6:7]
	v_lshl_add_u64 v[6:7], s[14:15], 0, v[6:7]
	v_mad_i64_i32 v[0:1], s[4:5], v4, s84, v[12:13]
	v_lshl_add_u64 v[0:1], v[0:1], 0, v[152:153]
	global_load_dword v26, v[0:1], off
	global_load_dword v27, v[0:1], off offset:1024
	global_load_dword v23, v[0:1], off offset:2048
	v_lshl_add_u64 v[0:1], s[12:13], 0, v[2:3]
	v_ashrrev_i32_e32 v2, 2, v11
	v_ashrrev_i32_e32 v3, 31, v2
	global_load_dword v24, v[0:1], off
	v_lshlrev_b64 v[0:1], 10, v[2:3]
	v_or_b32_e32 v16, v0, v152
	v_mov_b32_e32 v17, v1
	v_lshl_add_u64 v[0:1], s[8:9], 0, v[0:1]
	v_lshl_add_u64 v[0:1], v[0:1], 0, v[152:153]
	v_add_co_u32_e32 v0, vcc, s28, v0
	v_lshl_add_u64 v[18:19], s[8:9], 0, v[16:17]
	s_nop 0
	v_addc_co_u32_e32 v1, vcc, 0, v1, vcc
	global_load_dword v64, v[18:19], off
	v_add_u32_e32 v11, s22, v11
	global_load_dword v65, v[0:1], off
	v_lshlrev_b64 v[4:5], 11, v[4:5]
	v_lshl_add_u64 v[4:5], s[14:15], 0, v[4:5]
	v_mad_i64_i32 v[0:1], s[4:5], v2, s84, v[12:13]
	v_lshl_add_u64 v[0:1], v[0:1], 0, v[152:153]
	global_load_dword v21, v[0:1], off
	global_load_dword v22, v[0:1], off offset:1024
	global_load_dword v18, v[0:1], off offset:2048
	v_lshl_add_u64 v[0:1], s[12:13], 0, v[16:17]
	global_load_dword v19, v[0:1], off
	v_ashrrev_i32_e32 v0, 2, v11
	v_ashrrev_i32_e32 v1, 31, v0
	v_lshlrev_b64 v[16:17], 10, v[0:1]
	v_or_b32_e32 v32, v16, v152
	v_mov_b32_e32 v33, v17
	v_lshl_add_u64 v[16:17], s[8:9], 0, v[16:17]
	v_lshl_add_u64 v[16:17], v[16:17], 0, v[152:153]
	v_add_co_u32_e32 v16, vcc, s28, v16
	v_lshl_add_u64 v[34:35], s[8:9], 0, v[32:33]
	s_nop 0
	v_addc_co_u32_e32 v17, vcc, 0, v17, vcc
	global_load_dword v66, v[34:35], off
	v_mad_i64_i32 v[12:13], s[4:5], v0, s84, v[12:13]
	global_load_dword v67, v[16:17], off
	v_lshl_add_u64 v[12:13], v[12:13], 0, v[152:153]
	v_lshl_add_u64 v[32:33], s[12:13], 0, v[32:33]
	v_lshlrev_b32_e32 v152, 1, v28
	v_lshl_add_u64 v[6:7], v[6:7], 0, v[152:153]
	v_lshl_add_u64 v[4:5], v[4:5], 0, v[152:153]
	v_lshlrev_b64 v[2:3], 11, v[2:3]
	v_lshl_add_u64 v[2:3], s[14:15], 0, v[2:3]
	v_lshl_add_u64 v[2:3], v[2:3], 0, v[152:153]
	v_lshlrev_b64 v[0:1], 11, v[0:1]
	v_lshl_add_u64 v[0:1], s[14:15], 0, v[0:1]
	v_lshl_add_u64 v[0:1], v[0:1], 0, v[152:153]
	s_waitcnt vmcnt(0)
	v_add_f32_e32 v31, v60, v61
	v_add_f32_e32 v25, v62, v63
	v_add_f32_e32 v20, v64, v65
	v_add_f32_e32 v15, v66, v67
	global_load_dword v16, v[12:13], off
	global_load_dword v17, v[12:13], off offset:1024
	s_nop 0
	global_load_dword v12, v[12:13], off offset:2048
	s_nop 0
	global_load_dword v13, v[32:33], off
	v_add_f32_dpp v32, v31, v31 row_ror:8 row_mask:0xf bank_mask:0xf bound_ctrl:1
	s_nop 1
	v_add_f32_dpp v32, v32, v32 row_ror:4 row_mask:0xf bank_mask:0xf bound_ctrl:1
	s_nop 1
	v_add_f32_dpp v32, v32, v32 row_ror:2 row_mask:0xf bank_mask:0xf bound_ctrl:1
	s_nop 1
	v_add_f32_dpp v32, v32, v32 row_ror:1 row_mask:0xf bank_mask:0xf bound_ctrl:1
	v_mov_b32_e32 v33, v32
	s_nop 1
	v_permlane16_swap_b32_e32 v32, v33
	v_add_f32_e32 v32, v32, v33
	v_mov_b32_e32 v33, v32
	s_nop 1
	v_permlane32_swap_b32_e32 v32, v33
	v_add_f32_e32 v32, v32, v33
	v_fmac_f32_e32 v31, 0xbc800000, v32
	v_mul_f32_e32 v32, v31, v31
	v_mov_b32_e32 v33, v153
	s_nop 1
	v_mov_b32_dpp v33, v32 row_ror:8 row_mask:0xf bank_mask:0xf
	v_fmac_f32_e32 v33, v31, v31
	s_nop 1
	v_add_f32_dpp v32, v33, v33 row_ror:4 row_mask:0xf bank_mask:0xf bound_ctrl:1
	s_nop 1
	v_add_f32_dpp v32, v32, v32 row_ror:2 row_mask:0xf bank_mask:0xf bound_ctrl:1
	s_nop 1
	v_add_f32_dpp v32, v32, v32 row_ror:1 row_mask:0xf bank_mask:0xf bound_ctrl:1
	v_mov_b32_e32 v33, v32
	s_nop 1
	v_permlane16_swap_b32_e32 v32, v33
	v_add_f32_e32 v32, v32, v33
	v_mov_b32_e32 v33, v32
	s_nop 1
	v_permlane32_swap_b32_e32 v32, v33
	v_add_f32_e32 v32, v32, v33
	v_fmamk_f32 v32, v32, 0x3c800000, v198
	v_cmp_gt_f32_e32 vcc, s43, v32
	v_mul_f32_e32 v33, 0x4f800000, v32
	s_nop 0
	v_cndmask_b32_e32 v32, v32, v33, vcc
	v_sqrt_f32_e32 v33, v32
	s_nop 0
	v_add_u32_e32 v34, -1, v33
	v_fma_f32 v35, -v34, v33, v32
	v_cmp_ge_f32_e64 s[4:5], 0, v35
	v_add_u32_e32 v35, 1, v33
	s_nop 0
	v_cndmask_b32_e64 v34, v33, v34, s[4:5]
	v_fma_f32 v33, -v35, v33, v32
	v_cmp_lt_f32_e64 s[4:5], 0, v33
; __device__ __forceinline__ unsigned pk2(float lo, float hi) { return pg8::pk_bf16_rne(lo, hi); }
; __device__ __forceinline__ float wave_sum(float v) { v = row16_allsum(v); v = rows_pair_sum(v); v = halves_pair_sum(v); return v; }
; __device__ __forceinline__ void rwkv_post(const Params& P, int l, int gw, int NGW, int lane) {
;     ...
;         for (int q = 0; q < 4; ++q) { const int it = it0 + q * NGW; const size_t t = (size_t)(it >> 2); const int c = (it & 3) * 64 + lane;
;             const float mean = wave_sum(y[q]) * (1.0f / 64.0f);
;             const float dd = y[q] - mean;
;             const float var = wave_sum(dd * dd) * (1.0f / 64.0f);
;             const float yn = dd * (1.0f / sqrtf(var + 64e-5f)) * lg[q] + lb[q];
;             const float bonus = wave_sum(r[q] * k[q] * rk[q]) * v[q];
;             MIX[t * 1024 + c] = (bf16_t)(pk2((yn + bonus) * g[q], 0.f) & 0xffffu); }
	s_nop 1
	v_cndmask_b32_e64 v33, v34, v35, s[4:5]
	v_mul_f32_e32 v34, 0x37800000, v33
	v_cndmask_b32_e32 v33, v33, v34, vcc
	v_cmp_class_f32_e32 vcc, v32, v175
	s_nop 1
	v_cndmask_b32_e32 v32, v33, v32, vcc
	v_div_scale_f32 v33, s[4:5], v32, v32, 1.0
	v_rcp_f32_e32 v34, v33
	s_nop 0
	v_fma_f32 v35, -v33, v34, 1.0
	v_fmac_f32_e32 v34, v35, v34
	v_div_scale_f32 v35, vcc, 1.0, v32, 1.0
	v_mul_f32_e32 v38, v35, v34
	v_fma_f32 v39, -v33, v38, v35
	v_fmac_f32_e32 v38, v39, v34
	v_fma_f32 v33, -v33, v38, v35
	v_div_fmas_f32 v33, v33, v34, v38
	v_div_fixup_f32 v32, v33, v32, 1.0
	v_mul_f32_e32 v31, v31, v32
	v_mul_f32_e32 v32, v36, v37
	v_mul_f32_e32 v33, v32, v10
	v_mov_b32_e32 v34, v153
	v_fma_f32 v31, v14, v31, v9
	s_nop 0
	v_mov_b32_dpp v34, v33 row_ror:8 row_mask:0xf bank_mask:0xf
	v_fmac_f32_e32 v34, v32, v10
	s_nop 1
	v_add_f32_dpp v32, v34, v34 row_ror:4 row_mask:0xf bank_mask:0xf bound_ctrl:1
	s_nop 1
	v_add_f32_dpp v32, v32, v32 row_ror:2 row_mask:0xf bank_mask:0xf bound_ctrl:1
	s_nop 1
	v_add_f32_dpp v32, v32, v32 row_ror:1 row_mask:0xf bank_mask:0xf bound_ctrl:1
	v_mov_b32_e32 v33, v32
	s_nop 1
	v_permlane16_swap_b32_e32 v32, v33
	v_add_f32_e32 v32, v32, v33
	v_mov_b32_e32 v33, v32
	s_nop 1
	v_permlane32_swap_b32_e32 v32, v33
	v_add_f32_e32 v32, v32, v33
	v_fmac_f32_e32 v31, v29, v32
	v_mul_f32_e32 v29, v30, v31
	v_cvt_pk_bf16_f32 v29, v29, s0
	global_store_short v[6:7], v29, off
	v_add_f32_dpp v6, v25, v25 row_ror:8 row_mask:0xf bank_mask:0xf bound_ctrl:1
	s_nop 1
	v_add_f32_dpp v6, v6, v6 row_ror:4 row_mask:0xf bank_mask:0xf bound_ctrl:1
	s_nop 1
	v_add_f32_dpp v6, v6, v6 row_ror:2 row_mask:0xf bank_mask:0xf bound_ctrl:1
	s_nop 1
	v_add_f32_dpp v6, v6, v6 row_ror:1 row_mask:0xf bank_mask:0xf bound_ctrl:1
	v_mov_b32_e32 v7, v6
	s_nop 1
	v_permlane16_swap_b32_e32 v6, v7
	v_add_f32_e32 v6, v6, v7
	v_mov_b32_e32 v7, v6
	s_nop 1
	v_permlane32_swap_b32_e32 v6, v7
	v_add_f32_e32 v6, v6, v7
	v_fmac_f32_e32 v25, 0xbc800000, v6
	v_mul_f32_e32 v6, v25, v25
	v_mov_b32_e32 v7, v153
	s_nop 1
	v_mov_b32_dpp v7, v6 row_ror:8 row_mask:0xf bank_mask:0xf
	v_fmac_f32_e32 v7, v25, v25
	s_nop 1
	v_add_f32_dpp v6, v7, v7 row_ror:4 row_mask:0xf bank_mask:0xf bound_ctrl:1
	s_nop 1
	v_add_f32_dpp v6, v6, v6 row_ror:2 row_mask:0xf bank_mask:0xf bound_ctrl:1
	s_nop 1
	v_add_f32_dpp v6, v6, v6 row_ror:1 row_mask:0xf bank_mask:0xf bound_ctrl:1
	v_mov_b32_e32 v7, v6
	s_nop 1
	v_permlane16_swap_b32_e32 v6, v7
	v_add_f32_e32 v6, v6, v7
	v_mov_b32_e32 v7, v6
	s_nop 1
	v_permlane32_swap_b32_e32 v6, v7
	v_add_f32_e32 v6, v6, v7
	v_fmamk_f32 v6, v6, 0x3c800000, v198
	v_cmp_gt_f32_e32 vcc, s43, v6
	v_mul_f32_e32 v7, 0x4f800000, v6
	s_nop 0
	v_cndmask_b32_e32 v6, v6, v7, vcc
	v_sqrt_f32_e32 v7, v6
	s_nop 0
	v_add_u32_e32 v28, -1, v7
	v_fma_f32 v29, -v28, v7, v6
	v_cmp_ge_f32_e64 s[4:5], 0, v29
	v_add_u32_e32 v29, 1, v7
	s_nop 0
	v_cndmask_b32_e64 v28, v7, v28, s[4:5]
	v_fma_f32 v7, -v29, v7, v6
	v_cmp_lt_f32_e64 s[4:5], 0, v7
	s_nop 1
	v_cndmask_b32_e64 v7, v28, v29, s[4:5]
	v_mul_f32_e32 v28, 0x37800000, v7
	v_cndmask_b32_e32 v7, v7, v28, vcc
	v_cmp_class_f32_e32 vcc, v6, v175
	s_nop 1
	v_cndmask_b32_e32 v6, v7, v6, vcc
	v_div_scale_f32 v7, s[4:5], v6, v6, 1.0
	v_rcp_f32_e32 v28, v7
	s_nop 0
	v_fma_f32 v29, -v7, v28, 1.0
	v_fmac_f32_e32 v28, v29, v28
	v_div_scale_f32 v29, vcc, 1.0, v6, 1.0
	v_mul_f32_e32 v30, v29, v28
	v_fma_f32 v31, -v7, v30, v29
	v_fmac_f32_e32 v30, v31, v28
	v_fma_f32 v7, -v7, v30, v29
	v_div_fmas_f32 v7, v7, v28, v30
	v_div_fixup_f32 v6, v7, v6, 1.0
	v_mul_f32_e32 v7, v26, v27
	v_mul_f32_e32 v6, v25, v6
	v_mul_f32_e32 v25, v7, v10
	v_mov_b32_e32 v26, v153
	v_fma_f32 v6, v14, v6, v9
	s_nop 0
	v_mov_b32_dpp v26, v25 row_ror:8 row_mask:0xf bank_mask:0xf
	v_fmac_f32_e32 v26, v7, v10
	s_nop 1
	v_add_f32_dpp v7, v26, v26 row_ror:4 row_mask:0xf bank_mask:0xf bound_ctrl:1
	s_nop 1
	v_add_f32_dpp v7, v7, v7 row_ror:2 row_mask:0xf bank_mask:0xf bound_ctrl:1
	s_nop 1
	v_add_f32_dpp v7, v7, v7 row_ror:1 row_mask:0xf bank_mask:0xf bound_ctrl:1
	v_mov_b32_e32 v25, v7
	s_nop 1
	v_permlane16_swap_b32_e32 v7, v25
	v_add_f32_e32 v7, v7, v25
	v_mov_b32_e32 v25, v7
	s_nop 1
	v_permlane32_swap_b32_e32 v7, v25
	v_add_f32_e32 v7, v7, v25
	v_fmac_f32_e32 v6, v23, v7
	v_mul_f32_e32 v6, v24, v6
	v_cvt_pk_bf16_f32 v6, v6, s0
	global_store_short v[4:5], v6, off
	v_add_f32_dpp v4, v20, v20 row_ror:8 row_mask:0xf bank_mask:0xf bound_ctrl:1
	s_nop 1
	v_add_f32_dpp v4, v4, v4 row_ror:4 row_mask:0xf bank_mask:0xf bound_ctrl:1
	s_nop 1
	v_add_f32_dpp v4, v4, v4 row_ror:2 row_mask:0xf bank_mask:0xf bound_ctrl:1
	s_nop 1
	v_add_f32_dpp v4, v4, v4 row_ror:1 row_mask:0xf bank_mask:0xf bound_ctrl:1
	v_mov_b32_e32 v5, v4
	s_nop 1
	v_permlane16_swap_b32_e32 v4, v5
	v_add_f32_e32 v4, v4, v5
	v_mov_b32_e32 v5, v4
	s_nop 1
	v_permlane32_swap_b32_e32 v4, v5
	v_add_f32_e32 v4, v4, v5
	v_fmac_f32_e32 v20, 0xbc800000, v4
	v_mul_f32_e32 v4, v20, v20
	v_mov_b32_e32 v5, v153
	s_nop 1
	v_mov_b32_dpp v5, v4 row_ror:8 row_mask:0xf bank_mask:0xf
	v_fmac_f32_e32 v5, v20, v20
	s_nop 1
	v_add_f32_dpp v4, v5, v5 row_ror:4 row_mask:0xf bank_mask:0xf bound_ctrl:1
	s_nop 1
; __device__ __forceinline__ unsigned pk2(float lo, float hi) { return pg8::pk_bf16_rne(lo, hi); }
; __device__ __forceinline__ float wave_sum(float v) { v = row16_allsum(v); v = rows_pair_sum(v); v = halves_pair_sum(v); return v; }
; __device__ __forceinline__ void rwkv_post(const Params& P, int l, int gw, int NGW, int lane) {
;     ...
;         for (int q = 0; q < 4; ++q) { const int it = it0 + q * NGW; const size_t t = (size_t)(it >> 2); const int c = (it & 3) * 64 + lane;
;             const float mean = wave_sum(y[q]) * (1.0f / 64.0f);
;             const float dd = y[q] - mean;
;             const float var = wave_sum(dd * dd) * (1.0f / 64.0f);
;             const float yn = dd * (1.0f / sqrtf(var + 64e-5f)) * lg[q] + lb[q];
;             const float bonus = wave_sum(r[q] * k[q] * rk[q]) * v[q];
;             MIX[t * 1024 + c] = (bf16_t)(pk2((yn + bonus) * g[q], 0.f) & 0xffffu); }
	v_add_f32_dpp v4, v4, v4 row_ror:2 row_mask:0xf bank_mask:0xf bound_ctrl:1
	s_nop 1
	v_add_f32_dpp v4, v4, v4 row_ror:1 row_mask:0xf bank_mask:0xf bound_ctrl:1
	v_mov_b32_e32 v5, v4
	s_nop 1
	v_permlane16_swap_b32_e32 v4, v5
	v_add_f32_e32 v4, v4, v5
	v_mov_b32_e32 v5, v4
	s_nop 1
	v_permlane32_swap_b32_e32 v4, v5
	v_add_f32_e32 v4, v4, v5
	v_fmamk_f32 v4, v4, 0x3c800000, v198
	v_cmp_gt_f32_e32 vcc, s43, v4
	v_mul_f32_e32 v5, 0x4f800000, v4
	s_nop 0
	v_cndmask_b32_e32 v4, v4, v5, vcc
	v_sqrt_f32_e32 v5, v4
	s_nop 0
	v_add_u32_e32 v6, -1, v5
	v_fma_f32 v7, -v6, v5, v4
	v_cmp_ge_f32_e64 s[4:5], 0, v7
	v_add_u32_e32 v7, 1, v5
	s_nop 0
	v_cndmask_b32_e64 v6, v5, v6, s[4:5]
	v_fma_f32 v5, -v7, v5, v4
	v_cmp_lt_f32_e64 s[4:5], 0, v5
	s_nop 1
	v_cndmask_b32_e64 v5, v6, v7, s[4:5]
	v_mul_f32_e32 v6, 0x37800000, v5
	v_cndmask_b32_e32 v5, v5, v6, vcc
	v_cmp_class_f32_e32 vcc, v4, v175
	s_nop 1
	v_cndmask_b32_e32 v4, v5, v4, vcc
	v_div_scale_f32 v5, s[4:5], v4, v4, 1.0
	v_rcp_f32_e32 v6, v5
	s_nop 0
	v_fma_f32 v7, -v5, v6, 1.0
	v_fmac_f32_e32 v6, v7, v6
	v_div_scale_f32 v7, vcc, 1.0, v4, 1.0
	v_mul_f32_e32 v23, v7, v6
	v_fma_f32 v24, -v5, v23, v7
	v_fmac_f32_e32 v23, v24, v6
	v_fma_f32 v5, -v5, v23, v7
	v_div_fmas_f32 v5, v5, v6, v23
	v_div_fixup_f32 v4, v5, v4, 1.0
	v_mul_f32_e32 v5, v21, v22
	v_mul_f32_e32 v6, v5, v10
	v_mov_b32_e32 v7, v153
	v_mul_f32_e32 v4, v20, v4
	v_fma_f32 v4, v14, v4, v9
	v_mov_b32_dpp v7, v6 row_ror:8 row_mask:0xf bank_mask:0xf
	v_fmac_f32_e32 v7, v5, v10
	s_nop 1
	v_add_f32_dpp v5, v7, v7 row_ror:4 row_mask:0xf bank_mask:0xf bound_ctrl:1
	s_nop 1
	v_add_f32_dpp v5, v5, v5 row_ror:2 row_mask:0xf bank_mask:0xf bound_ctrl:1
	s_nop 1
	v_add_f32_dpp v5, v5, v5 row_ror:1 row_mask:0xf bank_mask:0xf bound_ctrl:1
	v_mov_b32_e32 v6, v5
	s_nop 1
	v_permlane16_swap_b32_e32 v5, v6
	v_add_f32_e32 v5, v5, v6
	v_mov_b32_e32 v6, v5
	s_nop 1
	v_permlane32_swap_b32_e32 v5, v6
	v_add_f32_e32 v5, v5, v6
	v_fmac_f32_e32 v4, v18, v5
	v_mul_f32_e32 v4, v19, v4
	v_cvt_pk_bf16_f32 v4, v4, s0
	global_store_short v[2:3], v4, off
	v_add_f32_dpp v2, v15, v15 row_ror:8 row_mask:0xf bank_mask:0xf bound_ctrl:1
	s_nop 1
	v_add_f32_dpp v2, v2, v2 row_ror:4 row_mask:0xf bank_mask:0xf bound_ctrl:1
	s_nop 1
	v_add_f32_dpp v2, v2, v2 row_ror:2 row_mask:0xf bank_mask:0xf bound_ctrl:1
	s_nop 1
	v_add_f32_dpp v2, v2, v2 row_ror:1 row_mask:0xf bank_mask:0xf bound_ctrl:1
	v_mov_b32_e32 v3, v2
	s_nop 1
	v_permlane16_swap_b32_e32 v2, v3
	v_add_f32_e32 v2, v2, v3
	v_mov_b32_e32 v3, v2
	s_nop 1
	v_permlane32_swap_b32_e32 v2, v3
	v_add_f32_e32 v2, v2, v3
	v_fmac_f32_e32 v15, 0xbc800000, v2
	v_mul_f32_e32 v2, v15, v15
	v_mov_b32_e32 v3, v153
	s_nop 1
	v_mov_b32_dpp v3, v2 row_ror:8 row_mask:0xf bank_mask:0xf
	v_fmac_f32_e32 v3, v15, v15
	s_nop 1
	v_add_f32_dpp v2, v3, v3 row_ror:4 row_mask:0xf bank_mask:0xf bound_ctrl:1
	s_nop 1
	v_add_f32_dpp v2, v2, v2 row_ror:2 row_mask:0xf bank_mask:0xf bound_ctrl:1
	s_nop 1
	v_add_f32_dpp v2, v2, v2 row_ror:1 row_mask:0xf bank_mask:0xf bound_ctrl:1
	v_mov_b32_e32 v3, v2
	s_nop 1
	v_permlane16_swap_b32_e32 v2, v3
	v_add_f32_e32 v2, v2, v3
	v_mov_b32_e32 v3, v2
	s_nop 1
	v_permlane32_swap_b32_e32 v2, v3
	v_add_f32_e32 v2, v2, v3
	v_fmamk_f32 v2, v2, 0x3c800000, v198
	v_cmp_gt_f32_e32 vcc, s43, v2
	v_mul_f32_e32 v3, 0x4f800000, v2
	s_nop 0
	v_cndmask_b32_e32 v2, v2, v3, vcc
	v_sqrt_f32_e32 v3, v2
	s_nop 0
	v_add_u32_e32 v4, -1, v3
	v_fma_f32 v5, -v4, v3, v2
	v_cmp_ge_f32_e64 s[4:5], 0, v5
	v_add_u32_e32 v5, 1, v3
	s_nop 0
	v_cndmask_b32_e64 v4, v3, v4, s[4:5]
	v_fma_f32 v3, -v5, v3, v2
	v_cmp_lt_f32_e64 s[4:5], 0, v3
	s_nop 1
	v_cndmask_b32_e64 v3, v4, v5, s[4:5]
	v_mul_f32_e32 v4, 0x37800000, v3
	v_cndmask_b32_e32 v3, v3, v4, vcc
	v_cmp_class_f32_e32 vcc, v2, v175
	s_nop 1
	v_cndmask_b32_e32 v2, v3, v2, vcc
	v_div_scale_f32 v3, s[4:5], v2, v2, 1.0
	v_rcp_f32_e32 v4, v3
	s_mov_b32 s4, 0xffff
	v_fma_f32 v5, -v3, v4, 1.0
	v_fmac_f32_e32 v4, v5, v4
	v_div_scale_f32 v5, vcc, 1.0, v2, 1.0
	v_mul_f32_e32 v6, v5, v4
	v_fma_f32 v7, -v3, v6, v5
	v_fmac_f32_e32 v6, v7, v4
	v_fma_f32 v3, -v3, v6, v5
	v_div_fmas_f32 v3, v3, v4, v6
	v_div_fixup_f32 v2, v3, v2, 1.0
	v_mul_f32_e32 v2, v15, v2
	v_fmac_f32_e32 v9, v14, v2
	s_waitcnt vmcnt(5)
	v_mul_f32_e32 v2, v16, v17
	v_mul_f32_e32 v3, v2, v10
	v_mov_b32_e32 v4, v153
	s_nop 1
	v_mov_b32_dpp v4, v3 row_ror:8 row_mask:0xf bank_mask:0xf
	v_fmac_f32_e32 v4, v2, v10
	s_nop 1
	v_add_f32_dpp v2, v4, v4 row_ror:4 row_mask:0xf bank_mask:0xf bound_ctrl:1
	s_nop 1
	v_add_f32_dpp v2, v2, v2 row_ror:2 row_mask:0xf bank_mask:0xf bound_ctrl:1
	s_nop 1
	v_add_f32_dpp v2, v2, v2 row_ror:1 row_mask:0xf bank_mask:0xf bound_ctrl:1
	v_mov_b32_e32 v3, v2
	s_nop 1
	v_permlane16_swap_b32_e32 v2, v3
	v_add_f32_e32 v2, v2, v3
	v_mov_b32_e32 v3, v2
	s_nop 1
	v_permlane32_swap_b32_e32 v2, v3
	v_add_f32_e32 v2, v2, v3
	s_waitcnt vmcnt(4)
	v_fmac_f32_e32 v9, v12, v2
	s_waitcnt vmcnt(3)
	v_mul_f32_e32 v2, v13, v9
	v_cvt_pk_bf16_f32 v2, v2, s0
	global_store_short v[0:1], v2, off
	v_add_u32_e32 v0, s22, v11
	v_cmp_lt_i32_e32 vcc, s4, v0
	s_or_b64 s[34:35], vcc, s[34:35]
	s_andn2_b64 exec, exec, s[34:35]
	s_cbranch_execnz .LBB0_62
